# attention loop: removed the s_nop 7 pad between the first two S1 MFMAs by moving its VALU consumer behind the S1 chain (hazard distances kept at 14 states)
# speedup vs baseline: 1.0033x; 1.0004x over previous
; DI void attn_phase(const bf16_t* __restrict__ qb, const bf16_t* __restrict__ kb, const bf16_t* __restrict__ vt, bf16_t* __restrict__ ob, ...
;     ...
;         for (int kt = 0; kt < nkt; ++kt) {
;             asm volatile("s_waitcnt vmcnt(8)" ::: "memory");
;             asm volatile("s_waitcnt lgkmcnt(0)" ::: "memory"); __builtin_amdgcn_s_barrier();
;             ATT_ISSUE(kt + 3, (kt + 3) & 3);
;             const char* cur = lds + (kt & 3) * 32768;
;             const char* kl = cur + c * 8192; const char* vl = cur + 16384;
;             f32x16 sacc[2];
;             {
;                 bf16x8 kfr[2][4];
; #pragma unroll
;                 for (int kf = 0; kf < 2; ++kf)
; #pragma unroll
;                     for (int s = 0; s < 4; ++s) kfr[kf][s] = ldfrag(kl, kf * 32 + l31, 2 * s + hh);
; #pragma unroll
;                 for (int kf = 0; kf < 2; ++kf) {
;                     sacc[kf] = MFMA(kfr[kf][0], qf[0], negm);
; #pragma unroll
;                     for (int s = 1; s < 4; ++s) sacc[kf] = MFMA(kfr[kf][s], qf[s], sacc[kf]);
;                 }
;             }
;             bf16x8 vf[2][4];
; #pragma unroll
;             for (int ef = 0; ef < 4; ++ef) vf[0][ef] = ldfrag(vl, ef * 32 + l31, hh);
;             __builtin_amdgcn_sched_group_barrier(0x100, 4, 0);
; #pragma unroll
;             for (int g_ = 0; g_ < 4; ++g_) { __builtin_amdgcn_sched_group_barrier(0x008, 1, 0); __builtin_amdgcn_sched_group_barrier(0x100, 1, 0); }
;             __builtin_amdgcn_sched_group_barrier(0x008, 4, 0);
;             __builtin_amdgcn_sched_group_barrier(0x100, 4, 0);
;             float mx = fmaxf(fmaxf(sacc[0][0], sacc[0][1]), sacc[0][2]);
; #pragma unroll
;             for (int i = 3; i < 15; i += 2) mx = fmaxf(fmaxf(mx, sacc[0][i]), sacc[0][i + 1]);
;             mx = fmaxf(fmaxf(mx, sacc[0][15]), sacc[1][0]);
; #pragma unroll
;             for (int i = 1; i < 15; i += 2) mx = fmaxf(fmaxf(mx, sacc[1][i]), sacc[1][i + 1]);
;             mx = fmaxf(mx, sacc[1][15]);
;             if (kt == 0 || __any(mx > 8.0f)) {
;                 const float mfull = fmaxf(mx, __shfl_xor(mx, 32));
;                 const float delta = kt == 0 ? mfull : fmaxf(mfull, 0.f);
;                 const float alpha = kt == 0 ? 1.0f : __builtin_amdgcn_exp2f(-delta);
;                 l_run *= alpha;
; #pragma unroll
;                 for (int ef = 0; ef < 4; ++ef)
; #pragma unroll
.LBB0_215:
	s_waitcnt vmcnt(8)
	s_waitcnt lgkmcnt(0)
	s_barrier
	s_add_i32 s17, s19, 0xfffe8000
	s_and_b32 s17, s17, 0x18000
	s_add_i32 s17, s17, 0
	v_add3_u32 v65, s17, v192, v193
	v_add_u32_e32 v130, v65, v194
	ds_read_b128 v[82:85], v130
	v_add_u32_e32 v134, v65, v198
	ds_read_b128 v[86:89], v134
	v_add_u32_e32 v138, v65, v199
	v_add_u32_e32 v65, v65, v200
	ds_read_b128 v[90:93], v138
	ds_read_b128 v[94:97], v65
	v_mfma_f32_32x32x16_bf16 v[0:15], v[204:207], v[220:223], v[0:15]
	v_mfma_f32_32x32x16_bf16 v[16:31], v[208:211], v[220:223], v[16:31]
	v_mfma_f32_32x32x16_bf16 v[32:47], v[212:215], v[220:223], v[32:47]
	v_mfma_f32_32x32x16_bf16 v[48:63], v[216:219], v[220:223], v[48:63]
	s_waitcnt lgkmcnt(3)
	v_mfma_f32_32x32x16_bf16 v[98:113], v[82:85], v[114:117], v[66:81]
	ds_read_b128 v[130:133], v130 offset:4096
	s_mov_b32 s20, 0x41000000
	s_waitcnt lgkmcnt(3)
	v_mfma_f32_32x32x16_bf16 v[98:113], v[86:89], v[118:121], v[98:113]
	ds_read_b128 v[134:137], v134 offset:4096
	s_waitcnt lgkmcnt(3)
	v_mfma_f32_32x32x16_bf16 v[98:113], v[90:93], v[122:125], v[98:113]
	ds_read_b128 v[138:141], v138 offset:4096
	s_waitcnt lgkmcnt(3)
	v_mfma_f32_32x32x16_bf16 v[98:113], v[94:97], v[126:129], v[98:113]
	ds_read_b128 v[142:145], v65 offset:4096
	v_add3_u32 v65, s17, v194, v193
	s_waitcnt lgkmcnt(3)
	v_mfma_f32_32x32x16_bf16 v[82:97], v[130:133], v[114:117], v[66:81]
	s_waitcnt lgkmcnt(2)
	v_mfma_f32_32x32x16_bf16 v[82:97], v[134:137], v[118:121], v[82:97]
	s_waitcnt lgkmcnt(1)
	v_mfma_f32_32x32x16_bf16 v[82:97], v[138:141], v[122:125], v[82:97]
	s_waitcnt lgkmcnt(0)
	v_mfma_f32_32x32x16_bf16 v[82:97], v[142:145], v[126:129], v[82:97]
	ds_read_b128 v[142:145], v65 offset:16384
	ds_read_b128 v[138:141], v65 offset:20480
	ds_read_b128 v[134:137], v65 offset:24576
	ds_read_b128 v[130:133], v65 offset:28672
	v_max_f32_e32 v146, v98, v98
	v_max_f32_e32 v65, v99, v99
	v_max_f32_e32 v65, v146, v65
	v_max3_f32 v65, v65, v100, v101
	v_max3_f32 v65, v65, v102, v103
	v_max3_f32 v65, v65, v104, v105
	v_max3_f32 v65, v65, v106, v107
	v_max3_f32 v65, v65, v108, v109
	v_max3_f32 v65, v65, v110, v111
	v_max3_f32 v65, v65, v112, v113
	v_max3_f32 v65, v65, v82, v83
	v_max3_f32 v65, v65, v84, v85
	v_max3_f32 v65, v65, v86, v87
	v_max3_f32 v65, v65, v88, v89
	v_max3_f32 v65, v65, v90, v91
	v_max3_f32 v65, v65, v92, v93
	v_max3_f32 v65, v65, v94, v95
	v_max3_f32 v65, v65, v96, v97
	v_cmp_lt_f32_e32 vcc, s20, v65
	s_cbranch_vccz .LBB0_214
	ds_bpermute_b32 v146, v190, v65
	s_waitcnt lgkmcnt(0)
	v_max3_f32 v146, v65, v146, 0
	v_exp_f32_e64 v172, -v146
	v_pk_add_f32 v[98:99], v[98:99], v[146:147] op_sel_hi:[1,0] neg_lo:[0,1] neg_hi:[0,1]
	v_pk_add_f32 v[100:101], v[100:101], v[146:147] op_sel_hi:[1,0] neg_lo:[0,1] neg_hi:[0,1]
	v_pk_add_f32 v[102:103], v[102:103], v[146:147] op_sel_hi:[1,0] neg_lo:[0,1] neg_hi:[0,1]
	v_pk_mul_f32 v[14:15], v[14:15], v[172:173] op_sel_hi:[1,0]
	v_pk_mul_f32 v[12:13], v[12:13], v[172:173] op_sel_hi:[1,0]
	v_pk_mul_f32 v[10:11], v[10:11], v[172:173] op_sel_hi:[1,0]
	v_pk_mul_f32 v[8:9], v[8:9], v[172:173] op_sel_hi:[1,0]
	v_pk_mul_f32 v[6:7], v[6:7], v[172:173] op_sel_hi:[1,0]
	v_pk_mul_f32 v[4:5], v[4:5], v[172:173] op_sel_hi:[1,0]
	v_pk_mul_f32 v[2:3], v[2:3], v[172:173] op_sel_hi:[1,0]
	v_pk_mul_f32 v[0:1], v[0:1], v[172:173] op_sel_hi:[1,0]
	v_pk_mul_f32 v[30:31], v[30:31], v[172:173] op_sel_hi:[1,0]
	v_pk_mul_f32 v[28:29], v[28:29], v[172:173] op_sel_hi:[1,0]
	v_pk_mul_f32 v[26:27], v[26:27], v[172:173] op_sel_hi:[1,0]
	v_pk_mul_f32 v[24:25], v[24:25], v[172:173] op_sel_hi:[1,0]
	v_pk_mul_f32 v[22:23], v[22:23], v[172:173] op_sel_hi:[1,0]
	v_pk_mul_f32 v[20:21], v[20:21], v[172:173] op_sel_hi:[1,0]
	v_pk_mul_f32 v[18:19], v[18:19], v[172:173] op_sel_hi:[1,0]
	v_pk_mul_f32 v[16:17], v[16:17], v[172:173] op_sel_hi:[1,0]
	v_pk_mul_f32 v[46:47], v[46:47], v[172:173] op_sel_hi:[1,0]
	v_pk_mul_f32 v[44:45], v[44:45], v[172:173] op_sel_hi:[1,0]
	v_pk_mul_f32 v[42:43], v[42:43], v[172:173] op_sel_hi:[1,0]
	v_pk_mul_f32 v[40:41], v[40:41], v[172:173] op_sel_hi:[1,0]
	v_pk_mul_f32 v[38:39], v[38:39], v[172:173] op_sel_hi:[1,0]
	v_pk_mul_f32 v[36:37], v[36:37], v[172:173] op_sel_hi:[1,0]
	v_pk_mul_f32 v[34:35], v[34:35], v[172:173] op_sel_hi:[1,0]
	v_pk_mul_f32 v[32:33], v[32:33], v[172:173] op_sel_hi:[1,0]
	v_pk_mul_f32 v[62:63], v[62:63], v[172:173] op_sel_hi:[1,0]
	v_pk_mul_f32 v[60:61], v[60:61], v[172:173] op_sel_hi:[1,0]
	v_pk_mul_f32 v[58:59], v[58:59], v[172:173] op_sel_hi:[1,0]
	v_pk_mul_f32 v[56:57], v[56:57], v[172:173] op_sel_hi:[1,0]
	v_pk_mul_f32 v[54:55], v[54:55], v[172:173] op_sel_hi:[1,0]
	v_pk_mul_f32 v[52:53], v[52:53], v[172:173] op_sel_hi:[1,0]
	v_pk_mul_f32 v[50:51], v[50:51], v[172:173] op_sel_hi:[1,0]
	v_pk_mul_f32 v[48:49], v[48:49], v[172:173] op_sel_hi:[1,0]
	v_pk_add_f32 v[104:105], v[104:105], v[146:147] op_sel_hi:[1,0] neg_lo:[0,1] neg_hi:[0,1]
	v_pk_add_f32 v[106:107], v[106:107], v[146:147] op_sel_hi:[1,0] neg_lo:[0,1] neg_hi:[0,1]
	v_pk_add_f32 v[108:109], v[108:109], v[146:147] op_sel_hi:[1,0] neg_lo:[0,1] neg_hi:[0,1]
	v_pk_add_f32 v[110:111], v[110:111], v[146:147] op_sel_hi:[1,0] neg_lo:[0,1] neg_hi:[0,1]
	v_sub_f32_e32 v81, v81, v146
	v_sub_f32_e32 v80, v80, v146
	v_sub_f32_e32 v79, v79, v146
	v_sub_f32_e32 v78, v78, v146
	v_sub_f32_e32 v77, v77, v146
	v_sub_f32_e32 v76, v76, v146
	v_sub_f32_e32 v75, v75, v146
	v_sub_f32_e32 v74, v74, v146
	v_sub_f32_e32 v73, v73, v146
	v_sub_f32_e32 v72, v72, v146
	v_sub_f32_e32 v71, v71, v146
	v_sub_f32_e32 v70, v70, v146
	v_sub_f32_e32 v69, v69, v146
	v_sub_f32_e32 v68, v68, v146
	v_sub_f32_e32 v67, v67, v146
	v_sub_f32_e32 v66, v66, v146
	v_pk_add_f32 v[112:113], v[112:113], v[146:147] op_sel_hi:[1,0] neg_lo:[0,1] neg_hi:[0,1]
	v_sub_f32_e32 v82, v82, v146
	v_sub_f32_e32 v83, v83, v146
	v_sub_f32_e32 v84, v84, v146
	v_sub_f32_e32 v85, v85, v146
	v_sub_f32_e32 v86, v86, v146
	v_sub_f32_e32 v87, v87, v146
	v_sub_f32_e32 v88, v88, v146
	v_sub_f32_e32 v89, v89, v146
	v_sub_f32_e32 v90, v90, v146
	v_sub_f32_e32 v91, v91, v146
	v_sub_f32_e32 v92, v92, v146
	v_sub_f32_e32 v93, v93, v146
	v_sub_f32_e32 v94, v94, v146
	v_sub_f32_e32 v95, v95, v146
	v_sub_f32_e32 v96, v96, v146
	v_sub_f32_e32 v97, v97, v146
	v_mul_f32_e32 v64, v64, v172
	s_branch .LBB0_214
